# attention QK: hoist K-fragment ds_reads into idle V/pb registers (bit-exact)
# speedup vs baseline: 1.0021x; 1.0021x over previous
.LBB0_362:
	s_and_b32 s14, s11, 1
	s_mul_i32 s12, s14, 0x4600
	s_add_i32 s15, s12, 16
	v_add3_u32 v160, s15, v209, v214
	ds_read_b128 v[96:99], v160
	ds_read_b128 v[224:227], v160 offset:4608
	ds_read_b128 v[228:231], v160 offset:32
	ds_read_b128 v[232:235], v160 offset:4640
	ds_read_b128 v[240:243], v160 offset:64
	ds_read_b128 v[248:251], v160 offset:4672
	v_mov_b64_e32 v[126:127], v[62:63]
	v_mov_b64_e32 v[124:125], v[60:61]
	v_mov_b64_e32 v[122:123], v[58:59]
	s_waitcnt lgkmcnt(5)
	v_mfma_f32_32x32x16_bf16 v[144:159], v[96:99], v[162:165], v[48:63]
	v_mov_b64_e32 v[120:121], v[56:57]
	v_mov_b64_e32 v[118:119], v[54:55]
	v_mov_b64_e32 v[116:117], v[52:53]
	v_mov_b64_e32 v[114:115], v[50:51]
	v_mov_b64_e32 v[112:113], v[48:49]
	v_mfma_f32_32x32x16_bf16 v[128:143], v[96:99], v[166:169], v[80:95]
	v_mov_b64_e32 v[110:111], v[94:95]
	v_mov_b64_e32 v[108:109], v[92:93]
	v_mov_b64_e32 v[106:107], v[90:91]
	v_mov_b64_e32 v[104:105], v[88:89]
	v_mov_b64_e32 v[102:103], v[86:87]
	v_mov_b64_e32 v[100:101], v[84:85]
	v_mov_b64_e32 v[98:99], v[82:83]
	v_mov_b64_e32 v[96:97], v[80:81]
	s_waitcnt lgkmcnt(4)
	v_mfma_f32_32x32x16_bf16 v[112:127], v[224:227], v[162:165], v[112:127]
	s_nop 0
	v_mfma_f32_32x32x16_bf16 v[96:111], v[224:227], v[166:169], v[96:111]
	ds_read_b128 v[224:227], v160 offset:96
	s_waitcnt lgkmcnt(4)
	v_mfma_f32_32x32x16_bf16 v[144:159], v[228:231], v[170:173], v[144:159]
	s_waitcnt lgkmcnt(3)
	v_mfma_f32_32x32x16_bf16 v[112:127], v[232:235], v[170:173], v[112:127]
	v_mfma_f32_32x32x16_bf16 v[128:143], v[228:231], v[174:177], v[128:143]
	v_mfma_f32_32x32x16_bf16 v[96:111], v[232:235], v[174:177], v[96:111]
	ds_read_b128 v[228:231], v160 offset:4704
	s_waitcnt lgkmcnt(3)
	v_mfma_f32_32x32x16_bf16 v[144:159], v[240:243], v[178:181], v[144:159]
	s_waitcnt lgkmcnt(2)
	v_mfma_f32_32x32x16_bf16 v[112:127], v[248:251], v[178:181], v[112:127]
	v_mfma_f32_32x32x16_bf16 v[128:143], v[240:243], v[186:189], v[128:143]
	v_mfma_f32_32x32x16_bf16 v[96:111], v[248:251], v[186:189], v[96:111]
	s_waitcnt lgkmcnt(1)
	v_mfma_f32_32x32x16_bf16 v[144:159], v[224:227], v[182:185], v[144:159]
	s_waitcnt lgkmcnt(0)
	v_mfma_f32_32x32x16_bf16 v[112:127], v[228:231], v[182:185], v[112:127]
	s_nop 9
	v_max_f32_e32 v160, v145, v145
	v_max_f32_e32 v215, v144, v144
	v_max_f32_e32 v160, v215, v160
	v_mfma_f32_32x32x16_bf16 v[128:143], v[224:227], v[190:193], v[128:143]
	v_max3_f32 v215, v146, v147, v113
	v_max3_f32 v160, v160, v112, v114
	v_max3_f32 v160, v160, v115, v148
	v_max3_f32 v215, v215, v150, v151
	v_max3_f32 v160, v160, v149, v116
	v_max3_f32 v215, v215, v118, v119
	v_max3_f32 v160, v160, v117, v152
	v_max3_f32 v215, v215, v154, v155
	v_max3_f32 v160, v160, v153, v120
	v_max3_f32 v215, v215, v122, v123
	v_mfma_f32_32x32x16_bf16 v[96:111], v[228:231], v[190:193], v[96:111]
	v_max3_f32 v160, v160, v121, v156
	v_max3_f32 v215, v215, v158, v159
	v_max3_f32 v160, v160, v157, v124
	v_max3_f32 v215, v215, v126, v127
	v_max3_f32 v160, v160, v125, v215
	v_mov_b32_e32 v215, v160
	s_nop 1
	v_permlane32_swap_b32_e32 v160, v215
	v_max_f32_e32 v215, v215, v215
	v_max_f32_e32 v160, v160, v160
	v_max_f32_e32 v160, v160, v215
	v_cmp_lt_f32_e32 vcc, s17, v160
	s_cbranch_vccz .LBB0_364
	v_max_f32_e32 v48, v160, v160
	v_max_f32_e32 v50, 0, v48
	v_exp_f32_e64 v51, -v50
	s_nop 0
	v_pk_add_f32 v[52:53], v[216:217], v[50:51]
	v_pk_mul_f32 v[48:49], v[216:217], v[50:51]
	v_pk_add_f32 v[144:145], v[144:145], v[50:51] op_sel_hi:[1,0] neg_lo:[0,1] neg_hi:[0,1]
	v_mov_b32_e32 v53, v49
	v_pk_add_f32 v[112:113], v[112:113], v[50:51] op_sel_hi:[1,0] neg_lo:[0,1] neg_hi:[0,1]
	v_pk_add_f32 v[48:49], v[52:53], 0 neg_lo:[1,1] neg_hi:[1,1]
	v_pk_add_f32 v[146:147], v[146:147], v[50:51] op_sel_hi:[1,0] neg_lo:[0,1] neg_hi:[0,1]
	v_pk_add_f32 v[114:115], v[114:115], v[50:51] op_sel_hi:[1,0] neg_lo:[0,1] neg_hi:[0,1]
	v_pk_add_f32 v[148:149], v[148:149], v[50:51] op_sel_hi:[1,0] neg_lo:[0,1] neg_hi:[0,1]
	v_pk_add_f32 v[116:117], v[116:117], v[50:51] op_sel_hi:[1,0] neg_lo:[0,1] neg_hi:[0,1]
	v_pk_add_f32 v[150:151], v[150:151], v[50:51] op_sel_hi:[1,0] neg_lo:[0,1] neg_hi:[0,1]
	v_pk_add_f32 v[118:119], v[118:119], v[50:51] op_sel_hi:[1,0] neg_lo:[0,1] neg_hi:[0,1]
	v_pk_add_f32 v[152:153], v[152:153], v[50:51] op_sel_hi:[1,0] neg_lo:[0,1] neg_hi:[0,1]
	v_pk_add_f32 v[120:121], v[120:121], v[50:51] op_sel_hi:[1,0] neg_lo:[0,1] neg_hi:[0,1]
	v_pk_add_f32 v[154:155], v[154:155], v[50:51] op_sel_hi:[1,0] neg_lo:[0,1] neg_hi:[0,1]
	v_pk_add_f32 v[122:123], v[122:123], v[50:51] op_sel_hi:[1,0] neg_lo:[0,1] neg_hi:[0,1]
	v_pk_add_f32 v[156:157], v[156:157], v[50:51] op_sel_hi:[1,0] neg_lo:[0,1] neg_hi:[0,1]
	v_pk_add_f32 v[124:125], v[124:125], v[50:51] op_sel_hi:[1,0] neg_lo:[0,1] neg_hi:[0,1]
	v_pk_add_f32 v[158:159], v[158:159], v[50:51] op_sel_hi:[1,0] neg_lo:[0,1] neg_hi:[0,1]
	v_pk_add_f32 v[126:127], v[126:127], v[50:51] op_sel_hi:[1,0] neg_lo:[0,1] neg_hi:[0,1]
	v_mov_b32_e32 v50, v51
	v_pk_mul_f32 v[78:79], v[78:79], v[50:51] op_sel_hi:[1,0]
	v_pk_mul_f32 v[76:77], v[76:77], v[50:51] op_sel_hi:[1,0]
	v_pk_mul_f32 v[74:75], v[74:75], v[50:51] op_sel_hi:[1,0]
	v_pk_mul_f32 v[72:73], v[72:73], v[50:51] op_sel_hi:[1,0]
	v_pk_mul_f32 v[70:71], v[70:71], v[50:51] op_sel_hi:[1,0]
	v_pk_mul_f32 v[68:69], v[68:69], v[50:51] op_sel_hi:[1,0]
	v_pk_mul_f32 v[66:67], v[66:67], v[50:51] op_sel_hi:[1,0]
	v_pk_mul_f32 v[64:65], v[64:65], v[50:51] op_sel_hi:[1,0]
	v_pk_mul_f32 v[14:15], v[14:15], v[50:51] op_sel_hi:[1,0]
	v_pk_mul_f32 v[12:13], v[12:13], v[50:51] op_sel_hi:[1,0]
	v_pk_mul_f32 v[10:11], v[10:11], v[50:51] op_sel_hi:[1,0]
	v_pk_mul_f32 v[8:9], v[8:9], v[50:51] op_sel_hi:[1,0]
	v_pk_mul_f32 v[6:7], v[6:7], v[50:51] op_sel_hi:[1,0]
	v_pk_mul_f32 v[4:5], v[4:5], v[50:51] op_sel_hi:[1,0]
	v_pk_mul_f32 v[2:3], v[2:3], v[50:51] op_sel_hi:[1,0]
	v_pk_mul_f32 v[0:1], v[0:1], v[50:51] op_sel_hi:[1,0]
	v_mov_b64_e32 v[216:217], v[52:53]
	v_mov_b32_e32 v49, v48
	v_mov_b32_e32 v50, v48
	v_mov_b32_e32 v51, v48
	v_mov_b32_e32 v52, v48
	v_mov_b32_e32 v53, v48
	v_mov_b32_e32 v54, v48
	v_mov_b32_e32 v55, v48
	v_mov_b32_e32 v56, v48
	v_mov_b32_e32 v57, v48
	v_mov_b32_e32 v58, v48
	v_mov_b32_e32 v59, v48
	v_mov_b32_e32 v60, v48
	v_mov_b32_e32 v61, v48
	v_mov_b32_e32 v62, v48
	v_mov_b32_e32 v63, v48
